# v21 plus: EpiGU SwiGLU chains evaluated four elements at a time with packed f32 mul/add around the same exp/rcp (same operation order per element; s_nop wait states filled with work)
# speedup vs baseline: 1.0077x; 1.0077x over previous
; __device__ __forceinline__ unsigned cvt_pk_bf16(float lo, float hi) { unsigned r; asm volatile("v_cvt_pk_bf16_f32 %0, %1, %2" : "=v"(r) : "v"(lo), "v"(hi)); return r; }
; __device__ __forceinline__ float fsilu(float x) { return x * fsigmoid(x); }
;     __device__ __forceinline__ void operator()(const f32x4 (&acc)[2][2][4][2], const Unit& u, int wr, int wc, int fr, int fq) const {
;         const int row0 = u.pm * 256 + wr * 64 + fr, col0 = u.pn * 128 + wc * 32 + 8 * fq;
; #pragma unroll
;         for (int ai = 0; ai < 2; ++ai)
; #pragma unroll
;             for (int m = 0; m < 4; ++m) { bf16* rowp = O + (size_t)(row0 + ai * 128 + m * 16) * DFF + col0;
;                 float h[8];
; #pragma unroll
;                 for (int n = 0; n < 2; ++n)
; #pragma unroll
;                     for (int i = 0; i < 4; ++i) h[4 * n + i] = fsilu(acc[ai][0][m][n][i]) * acc[ai][1][m][n][i];
;                 u32x4 w; w.x = cvt_pk_bf16(h[0], h[1]); w.y = cvt_pk_bf16(h[2], h[3]); w.z = cvt_pk_bf16(h[4], h[5]); w.w = cvt_pk_bf16(h[6], h[7]);
;                 asm volatile("global_store_dwordx4 %0, %1, off sc1\n\ts_nop 1" :: "v"(rowp), "v"(w) : "memory"); }
.Lgu_no_pending:
	s_mov_b32 s98, 0xbfb8aa3b
	s_mov_b32 s99, 0xbfb8aa3b
	s_mov_b32 s100, 1.0
	s_mov_b32 s101, 1.0
	v_pk_mul_f32 v[240:241], v[124:125], s[98:99]
	v_pk_mul_f32 v[242:243], v[126:127], s[98:99]
	v_exp_f32_e32 v240, v240
	v_exp_f32_e32 v241, v241
	v_exp_f32_e32 v242, v242
	v_exp_f32_e32 v243, v243
	v_pk_add_f32 v[240:241], v[240:241], s[100:101]
	v_pk_add_f32 v[242:243], v[242:243], s[100:101]
	v_rcp_f32_e32 v240, v240
	v_rcp_f32_e32 v241, v241
	v_rcp_f32_e32 v242, v242
	v_rcp_f32_e32 v243, v243
	v_pk_mul_f32 v[240:241], v[124:125], v[240:241]
	v_pk_mul_f32 v[242:243], v[126:127], v[242:243]
	v_pk_mul_f32 v[240:241], v[240:241], v[120:121]
	v_pk_mul_f32 v[242:243], v[242:243], v[122:123]
	v_lshl_or_b32 v146, s62, 7, v142
	v_lshl_add_u32 v144, s36, 8, v140
	v_ashrrev_i32_e32 v147, 31, v146
	v_mov_b64_e32 v[138:139], s[46:47]
	v_mad_i64_i32 v[148:149], s[16:17], v144, s92, v[138:139]
	v_pk_mul_f32 v[236:237], v[116:117], s[98:99]
	v_pk_mul_f32 v[238:239], v[118:119], s[98:99]
	v_exp_f32_e32 v236, v236
	v_exp_f32_e32 v237, v237
	v_exp_f32_e32 v238, v238
	v_exp_f32_e32 v239, v239
	v_pk_add_f32 v[236:237], v[236:237], s[100:101]
	v_pk_add_f32 v[238:239], v[238:239], s[100:101]
	v_rcp_f32_e32 v236, v236
	v_rcp_f32_e32 v237, v237
	v_rcp_f32_e32 v238, v238
	v_rcp_f32_e32 v239, v239
	v_pk_mul_f32 v[236:237], v[116:117], v[236:237]
	v_pk_mul_f32 v[238:239], v[118:119], v[238:239]
	v_pk_mul_f32 v[236:237], v[236:237], v[112:113]
	v_pk_mul_f32 v[238:239], v[238:239], v[114:115]
	v_cvt_pk_bf16_f32 v114, v240, v241
	s_nop 0
	v_lshlrev_b64 v[112:113], 1, v[146:147]
	v_cvt_pk_bf16_f32 v115, v242, v243
	v_cvt_pk_bf16_f32 v116, v236, v237
	v_lshl_add_u64 v[118:119], v[148:149], 0, v[112:113]
	v_cvt_pk_bf16_f32 v117, v238, v239
	s_nop 0
	global_store_dwordx4 v[118:119], v[114:117], off sc1
	s_nop 1
	v_pk_mul_f32 v[232:233], v[108:109], s[98:99]
	v_pk_mul_f32 v[234:235], v[110:111], s[98:99]
	v_exp_f32_e32 v232, v232
	v_exp_f32_e32 v233, v233
	v_exp_f32_e32 v234, v234
	v_exp_f32_e32 v235, v235
	v_pk_add_f32 v[232:233], v[232:233], s[100:101]
	v_pk_add_f32 v[234:235], v[234:235], s[100:101]
	v_rcp_f32_e32 v232, v232
	v_rcp_f32_e32 v233, v233
	v_rcp_f32_e32 v234, v234
	v_rcp_f32_e32 v235, v235
	v_pk_mul_f32 v[232:233], v[108:109], v[232:233]
	v_pk_mul_f32 v[234:235], v[110:111], v[234:235]
	v_pk_mul_f32 v[232:233], v[232:233], v[104:105]
	v_pk_mul_f32 v[234:235], v[234:235], v[106:107]
	v_or_b32_e32 v114, 16, v144
	v_mad_i64_i32 v[114:115], s[16:17], v114, s92, v[138:139]
	v_pk_mul_f32 v[228:229], v[100:101], s[98:99]
	v_pk_mul_f32 v[230:231], v[102:103], s[98:99]
	v_exp_f32_e32 v228, v228
	v_exp_f32_e32 v229, v229
	v_exp_f32_e32 v230, v230
	v_exp_f32_e32 v231, v231
	v_pk_add_f32 v[228:229], v[228:229], s[100:101]
	v_pk_add_f32 v[230:231], v[230:231], s[100:101]
	v_rcp_f32_e32 v228, v228
	v_rcp_f32_e32 v229, v229
	v_rcp_f32_e32 v230, v230
	v_rcp_f32_e32 v231, v231
	v_pk_mul_f32 v[228:229], v[100:101], v[228:229]
	v_pk_mul_f32 v[230:231], v[102:103], v[230:231]
	v_pk_mul_f32 v[228:229], v[228:229], v[96:97]
	v_pk_mul_f32 v[230:231], v[230:231], v[98:99]
	v_lshl_add_u64 v[100:101], v[114:115], 0, v[112:113]
	v_cvt_pk_bf16_f32 v96, v232, v233
	v_cvt_pk_bf16_f32 v97, v234, v235
	v_cvt_pk_bf16_f32 v98, v228, v229
	v_cvt_pk_bf16_f32 v99, v230, v231
	s_nop 0
	global_store_dwordx4 v[100:101], v[96:99], off sc1
	s_nop 1
	v_pk_mul_f32 v[224:225], v[92:93], s[98:99]
	v_pk_mul_f32 v[226:227], v[94:95], s[98:99]
	v_exp_f32_e32 v224, v224
	v_exp_f32_e32 v225, v225
	v_exp_f32_e32 v226, v226
	v_exp_f32_e32 v227, v227
	v_pk_add_f32 v[224:225], v[224:225], s[100:101]
	v_pk_add_f32 v[226:227], v[226:227], s[100:101]
	v_rcp_f32_e32 v224, v224
	v_rcp_f32_e32 v225, v225
	v_rcp_f32_e32 v226, v226
	v_rcp_f32_e32 v227, v227
	v_pk_mul_f32 v[224:225], v[92:93], v[224:225]
	v_pk_mul_f32 v[226:227], v[94:95], v[226:227]
	v_pk_mul_f32 v[224:225], v[224:225], v[88:89]
	v_pk_mul_f32 v[226:227], v[226:227], v[90:91]
	v_or_b32_e32 v96, 32, v144
	v_mad_i64_i32 v[96:97], s[16:17], v96, s92, v[138:139]
	v_pk_mul_f32 v[210:211], v[84:85], s[98:99]
	v_pk_mul_f32 v[212:213], v[86:87], s[98:99]
	v_exp_f32_e32 v210, v210
	v_exp_f32_e32 v211, v211
	v_exp_f32_e32 v212, v212
	v_exp_f32_e32 v213, v213
	v_pk_add_f32 v[210:211], v[210:211], s[100:101]
	v_pk_add_f32 v[212:213], v[212:213], s[100:101]
	v_rcp_f32_e32 v210, v210
	v_rcp_f32_e32 v211, v211
	v_rcp_f32_e32 v212, v212
	v_rcp_f32_e32 v213, v213
	v_pk_mul_f32 v[210:211], v[84:85], v[210:211]
	v_pk_mul_f32 v[212:213], v[86:87], v[212:213]
	v_pk_mul_f32 v[210:211], v[210:211], v[80:81]
	v_pk_mul_f32 v[212:213], v[212:213], v[82:83]
	v_lshl_add_u64 v[84:85], v[96:97], 0, v[112:113]
	v_cvt_pk_bf16_f32 v80, v224, v225
	v_cvt_pk_bf16_f32 v81, v226, v227
	v_cvt_pk_bf16_f32 v82, v210, v211
	v_cvt_pk_bf16_f32 v83, v212, v213
	s_nop 0
	global_store_dwordx4 v[84:85], v[80:83], off sc1
	s_nop 1
	v_pk_mul_f32 v[206:207], v[76:77], s[98:99]
	v_pk_mul_f32 v[208:209], v[78:79], s[98:99]
	v_exp_f32_e32 v206, v206
	v_exp_f32_e32 v207, v207
	v_exp_f32_e32 v208, v208
	v_exp_f32_e32 v209, v209
	v_pk_add_f32 v[206:207], v[206:207], s[100:101]
	v_pk_add_f32 v[208:209], v[208:209], s[100:101]
	v_rcp_f32_e32 v206, v206
	v_rcp_f32_e32 v207, v207
	v_rcp_f32_e32 v208, v208
	v_rcp_f32_e32 v209, v209
	v_pk_mul_f32 v[206:207], v[76:77], v[206:207]
	v_pk_mul_f32 v[208:209], v[78:79], v[208:209]
	v_pk_mul_f32 v[206:207], v[206:207], v[72:73]
	v_pk_mul_f32 v[208:209], v[208:209], v[74:75]
	v_or_b32_e32 v80, 48, v144
	v_mad_i64_i32 v[80:81], s[16:17], v80, s92, v[138:139]
	v_pk_mul_f32 v[202:203], v[68:69], s[98:99]
	v_pk_mul_f32 v[204:205], v[70:71], s[98:99]
; __device__ __forceinline__ unsigned cvt_pk_bf16(float lo, float hi) { unsigned r; asm volatile("v_cvt_pk_bf16_f32 %0, %1, %2" : "=v"(r) : "v"(lo), "v"(hi)); return r; }
; __device__ __forceinline__ float fsilu(float x) { return x * fsigmoid(x); }
;     __device__ __forceinline__ void operator()(const f32x4 (&acc)[2][2][4][2], const Unit& u, int wr, int wc, int fr, int fq) const {
;         const int row0 = u.pm * 256 + wr * 64 + fr, col0 = u.pn * 128 + wc * 32 + 8 * fq;
; #pragma unroll
;         for (int ai = 0; ai < 2; ++ai)
; #pragma unroll
;             for (int m = 0; m < 4; ++m) { bf16* rowp = O + (size_t)(row0 + ai * 128 + m * 16) * DFF + col0;
;                 float h[8];
; #pragma unroll
;                 for (int n = 0; n < 2; ++n)
; #pragma unroll
;                     for (int i = 0; i < 4; ++i) h[4 * n + i] = fsilu(acc[ai][0][m][n][i]) * acc[ai][1][m][n][i];
;                 u32x4 w; w.x = cvt_pk_bf16(h[0], h[1]); w.y = cvt_pk_bf16(h[2], h[3]); w.z = cvt_pk_bf16(h[4], h[5]); w.w = cvt_pk_bf16(h[6], h[7]);
;                 asm volatile("global_store_dwordx4 %0, %1, off sc1\n\ts_nop 1" :: "v"(rowp), "v"(w) : "memory"); }
	v_exp_f32_e32 v202, v202
	v_exp_f32_e32 v203, v203
	v_exp_f32_e32 v204, v204
	v_exp_f32_e32 v205, v205
	v_pk_add_f32 v[202:203], v[202:203], s[100:101]
	v_pk_add_f32 v[204:205], v[204:205], s[100:101]
	v_rcp_f32_e32 v202, v202
	v_rcp_f32_e32 v203, v203
	v_rcp_f32_e32 v204, v204
	v_rcp_f32_e32 v205, v205
	v_pk_mul_f32 v[202:203], v[68:69], v[202:203]
	v_pk_mul_f32 v[204:205], v[70:71], v[204:205]
	v_pk_mul_f32 v[202:203], v[202:203], v[64:65]
	v_pk_mul_f32 v[204:205], v[204:205], v[66:67]
	v_lshl_add_u64 v[68:69], v[80:81], 0, v[112:113]
	v_cvt_pk_bf16_f32 v64, v206, v207
	v_cvt_pk_bf16_f32 v65, v208, v209
	v_cvt_pk_bf16_f32 v66, v202, v203
	v_cvt_pk_bf16_f32 v67, v204, v205
	s_nop 0
	global_store_dwordx4 v[68:69], v[64:67], off sc1
	s_nop 1
	v_pk_mul_f32 v[198:199], v[60:61], s[98:99]
	v_pk_mul_f32 v[200:201], v[62:63], s[98:99]
	v_exp_f32_e32 v198, v198
	v_exp_f32_e32 v199, v199
	v_exp_f32_e32 v200, v200
	v_exp_f32_e32 v201, v201
	v_pk_add_f32 v[198:199], v[198:199], s[100:101]
	v_pk_add_f32 v[200:201], v[200:201], s[100:101]
	v_rcp_f32_e32 v198, v198
	v_rcp_f32_e32 v199, v199
	v_rcp_f32_e32 v200, v200
	v_rcp_f32_e32 v201, v201
	v_pk_mul_f32 v[198:199], v[60:61], v[198:199]
	v_pk_mul_f32 v[200:201], v[62:63], v[200:201]
	v_pk_mul_f32 v[198:199], v[198:199], v[56:57]
	v_pk_mul_f32 v[200:201], v[200:201], v[58:59]
	v_add_u32_e32 v64, 0x80, v144
	v_mad_i64_i32 v[64:65], s[16:17], v64, s92, v[138:139]
	v_pk_mul_f32 v[192:193], v[52:53], s[98:99]
	v_pk_mul_f32 v[194:195], v[54:55], s[98:99]
	v_exp_f32_e32 v192, v192
	v_exp_f32_e32 v193, v193
	v_exp_f32_e32 v194, v194
	v_exp_f32_e32 v195, v195
	v_pk_add_f32 v[192:193], v[192:193], s[100:101]
	v_pk_add_f32 v[194:195], v[194:195], s[100:101]
	v_rcp_f32_e32 v192, v192
	v_rcp_f32_e32 v193, v193
	v_rcp_f32_e32 v194, v194
	v_rcp_f32_e32 v195, v195
	v_pk_mul_f32 v[192:193], v[52:53], v[192:193]
	v_pk_mul_f32 v[194:195], v[54:55], v[194:195]
	v_pk_mul_f32 v[192:193], v[192:193], v[48:49]
	v_pk_mul_f32 v[194:195], v[194:195], v[50:51]
	v_lshl_add_u64 v[52:53], v[64:65], 0, v[112:113]
	v_cvt_pk_bf16_f32 v48, v198, v199
	v_cvt_pk_bf16_f32 v49, v200, v201
	v_cvt_pk_bf16_f32 v50, v192, v193
	v_cvt_pk_bf16_f32 v51, v194, v195
	s_nop 0
	global_store_dwordx4 v[52:53], v[48:51], off sc1
	s_nop 1
	v_pk_mul_f32 v[170:171], v[44:45], s[98:99]
	v_pk_mul_f32 v[190:191], v[46:47], s[98:99]
	v_exp_f32_e32 v170, v170
	v_exp_f32_e32 v171, v171
	v_exp_f32_e32 v190, v190
	v_exp_f32_e32 v191, v191
	v_pk_add_f32 v[170:171], v[170:171], s[100:101]
	v_pk_add_f32 v[190:191], v[190:191], s[100:101]
	v_rcp_f32_e32 v170, v170
	v_rcp_f32_e32 v171, v171
	v_rcp_f32_e32 v190, v190
	v_rcp_f32_e32 v191, v191
	v_pk_mul_f32 v[170:171], v[44:45], v[170:171]
	v_pk_mul_f32 v[190:191], v[46:47], v[190:191]
	v_pk_mul_f32 v[170:171], v[170:171], v[40:41]
	v_pk_mul_f32 v[190:191], v[190:191], v[42:43]
	v_add_u32_e32 v48, 0x90, v144
	v_mad_i64_i32 v[48:49], s[16:17], v48, s92, v[138:139]
	v_pk_mul_f32 v[166:167], v[36:37], s[98:99]
	v_pk_mul_f32 v[168:169], v[38:39], s[98:99]
	v_exp_f32_e32 v166, v166
	v_exp_f32_e32 v167, v167
	v_exp_f32_e32 v168, v168
	v_exp_f32_e32 v169, v169
	v_pk_add_f32 v[166:167], v[166:167], s[100:101]
	v_pk_add_f32 v[168:169], v[168:169], s[100:101]
	v_rcp_f32_e32 v166, v166
	v_rcp_f32_e32 v167, v167
	v_rcp_f32_e32 v168, v168
	v_rcp_f32_e32 v169, v169
	v_pk_mul_f32 v[166:167], v[36:37], v[166:167]
	v_pk_mul_f32 v[168:169], v[38:39], v[168:169]
	v_pk_mul_f32 v[166:167], v[166:167], v[32:33]
	v_pk_mul_f32 v[168:169], v[168:169], v[34:35]
	v_lshl_add_u64 v[36:37], v[48:49], 0, v[112:113]
	v_cvt_pk_bf16_f32 v32, v170, v171
	v_cvt_pk_bf16_f32 v33, v190, v191
	v_cvt_pk_bf16_f32 v34, v166, v167
	v_cvt_pk_bf16_f32 v35, v168, v169
	s_nop 0
	global_store_dwordx4 v[36:37], v[32:35], off sc1
	s_nop 1
	v_pk_mul_f32 v[162:163], v[28:29], s[98:99]
	v_pk_mul_f32 v[164:165], v[30:31], s[98:99]
	v_exp_f32_e32 v162, v162
	v_exp_f32_e32 v163, v163
	v_exp_f32_e32 v164, v164
	v_exp_f32_e32 v165, v165
	v_pk_add_f32 v[162:163], v[162:163], s[100:101]
	v_pk_add_f32 v[164:165], v[164:165], s[100:101]
	v_rcp_f32_e32 v162, v162
	v_rcp_f32_e32 v163, v163
	v_rcp_f32_e32 v164, v164
	v_rcp_f32_e32 v165, v165
	v_pk_mul_f32 v[162:163], v[28:29], v[162:163]
	v_pk_mul_f32 v[164:165], v[30:31], v[164:165]
	v_pk_mul_f32 v[162:163], v[162:163], v[24:25]
	v_pk_mul_f32 v[164:165], v[164:165], v[26:27]
	v_add_u32_e32 v32, 0xa0, v144
	v_mad_i64_i32 v[32:33], s[16:17], v32, s92, v[138:139]
	v_pk_mul_f32 v[158:159], v[20:21], s[98:99]
	v_pk_mul_f32 v[160:161], v[22:23], s[98:99]
	v_exp_f32_e32 v158, v158
	v_exp_f32_e32 v159, v159
	v_exp_f32_e32 v160, v160
	v_exp_f32_e32 v161, v161
	v_pk_add_f32 v[158:159], v[158:159], s[100:101]
	v_pk_add_f32 v[160:161], v[160:161], s[100:101]
	v_rcp_f32_e32 v158, v158
	v_rcp_f32_e32 v159, v159
	v_rcp_f32_e32 v160, v160
	v_rcp_f32_e32 v161, v161
	v_pk_mul_f32 v[158:159], v[20:21], v[158:159]
	v_pk_mul_f32 v[160:161], v[22:23], v[160:161]
	v_pk_mul_f32 v[158:159], v[158:159], v[16:17]
	v_pk_mul_f32 v[160:161], v[160:161], v[18:19]
	v_lshl_add_u64 v[20:21], v[32:33], 0, v[112:113]
	v_cvt_pk_bf16_f32 v16, v162, v163
	v_cvt_pk_bf16_f32 v17, v164, v165
	v_cvt_pk_bf16_f32 v18, v158, v159
	v_cvt_pk_bf16_f32 v19, v160, v161
	s_nop 0
	global_store_dwordx4 v[20:21], v[16:19], off sc1
	s_nop 1
	v_pk_mul_f32 v[154:155], v[12:13], s[98:99]
	v_pk_mul_f32 v[156:157], v[14:15], s[98:99]
	v_exp_f32_e32 v154, v154
	v_exp_f32_e32 v155, v155
	v_exp_f32_e32 v156, v156
	v_exp_f32_e32 v157, v157
	v_pk_add_f32 v[154:155], v[154:155], s[100:101]
	v_pk_add_f32 v[156:157], v[156:157], s[100:101]
	v_rcp_f32_e32 v154, v154
	v_rcp_f32_e32 v155, v155
	v_rcp_f32_e32 v156, v156
	v_rcp_f32_e32 v157, v157
	v_pk_mul_f32 v[154:155], v[12:13], v[154:155]
	v_pk_mul_f32 v[156:157], v[14:15], v[156:157]
	v_pk_mul_f32 v[154:155], v[154:155], v[8:9]
	v_pk_mul_f32 v[156:157], v[156:157], v[10:11]
	v_add_u32_e32 v16, 0xb0, v144
	v_mad_i64_i32 v[16:17], s[16:17], v16, s92, v[138:139]
	v_pk_mul_f32 v[150:151], v[4:5], s[98:99]
	v_pk_mul_f32 v[152:153], v[6:7], s[98:99]
	v_exp_f32_e32 v150, v150
	v_exp_f32_e32 v151, v151
	v_exp_f32_e32 v152, v152
	v_exp_f32_e32 v153, v153
	v_pk_add_f32 v[150:151], v[150:151], s[100:101]
	v_pk_add_f32 v[152:153], v[152:153], s[100:101]
	v_rcp_f32_e32 v150, v150
	v_rcp_f32_e32 v151, v151
	v_rcp_f32_e32 v152, v152
	v_rcp_f32_e32 v153, v153
	v_pk_mul_f32 v[150:151], v[4:5], v[150:151]
	v_pk_mul_f32 v[152:153], v[6:7], v[152:153]
	v_pk_mul_f32 v[150:151], v[150:151], v[0:1]
	v_pk_mul_f32 v[152:153], v[152:153], v[2:3]
	v_lshl_add_u64 v[4:5], v[16:17], 0, v[112:113]
	v_cvt_pk_bf16_f32 v0, v154, v155
	v_cvt_pk_bf16_f32 v1, v156, v157
	v_cvt_pk_bf16_f32 v2, v150, v151
	v_cvt_pk_bf16_f32 v3, v152, v153
	s_nop 0
	global_store_dwordx4 v[4:5], v[0:3], off sc1
	s_nop 1
	s_and_b64 vcc, exec, s[56:57]
	s_cbranch_vccz .Lgu_drain_now
	v_writelane_b32 v250, s36, 0
	s_branch .Lgu_defer_join
